# C loops: s_setprio 0 during PV MFMA phase, 1 during softmax/QK phases (on top of out-of-phase wave halves)
# speedup vs baseline: 1.1277x; 1.0039x over previous
; #define SBAR() __builtin_amdgcn_sched_barrier(0)
; template <int MODE>
; __device__ __forceinline__ void partialSM(f32x16& p0, f32x16& p1, float& m_reg, float& mn, float& alpha, int relh, int relw_min, int relw_max, const float* lut) {
;     ...
;     if (nearT) {
; #pragma unroll
;       for (int r = 0; r < 16; ++r) { const int i0 = relh + (r & 3) + 8 * (r >> 2);
;         const int a0 = min(max(i0, -129), 129) + 129, a1 = min(max(i0 + 32, -129), 129) + 129;
;         p0[r] = fmaf(p0[r], C, lut[a0]); p1[r] = fmaf(p1[r], C, lut[a1]); }
;     } else {
; #pragma unroll
;       for (int r = 0; r < 16; ++r) { p0[r] = fmaf(p0[r], C, cfar); p1[r] = fmaf(p1[r], C, cfar); }
; __device__ __forceinline__ int v_st(int k, int c) { const int kk = (k & ~0xC) | ((k & 4) << 1) | ((k & 8) >> 1); return ((kk >> 3) * 4 + (c >> 5)) * 512 + ((kk & 7) * 32 + (c & 31)) * 2; }
; __device__ __forceinline__ int v_rd_base(int lane) { return ((lane & 3) << 3) | (((lane >> 2) & 3) << 6) | (((lane >> 4) & 1) << 5) | (((lane >> 5) & 1) << 8); }
; template <int OFF> __device__ __forceinline__ s16x4 tr_read(int vb) {
;   s16x4 r; asm volatile("ds_read_b64_tr_b16 %0, %1 offset:%2" : "=&v"(r) : "v"(vb), "i"(OFF) : "memory"); return r;
; }
; template <int D0> __device__ __forceinline__ void pv_one(f32x16& od, int vb, bf16x8 pa0, bf16x8 pa1, bf16x8 pa2, bf16x8 pa3) {
;   const s16x4 l0 = tr_read<v_rd_off(D0, 0, 0)>(vb), h0 = tr_read<v_rd_off(D0, 0, 1)>(vb), l1 = tr_read<v_rd_off(D0, 1, 0)>(vb), h1 = tr_read<v_rd_off(D0, 1, 1)>(vb);
;   const s16x4 l2 = tr_read<v_rd_off(D0, 2, 0)>(vb), h2 = tr_read<v_rd_off(D0, 2, 1)>(vb), l3 = tr_read<v_rd_off(D0, 3, 0)>(vb), h3 = tr_read<v_rd_off(D0, 3, 1)>(vb);
;   asm volatile("s_waitcnt lgkmcnt(0)" ::: "memory"); SBAR();
;     ...
;   od = __builtin_amdgcn_mfma_f32_32x32x16_bf16(pa0, PK(l0, h0), od, 0, 0, 0);
;   od = __builtin_amdgcn_mfma_f32_32x32x16_bf16(pa1, PK(l1, h1), od, 0, 0, 0);
;   od = __builtin_amdgcn_mfma_f32_32x32x16_bf16(pa2, PK(l2, h2), od, 0, 0, 0);
;   od = __builtin_amdgcn_mfma_f32_32x32x16_bf16(pa3, PK(l3, h3), od, 0, 0, 0);
;     ...
; }
; __device__ __forceinline__ void pv_d0(f32x16* o, int vb, bf16x8 pa0, bf16x8 pa1, bf16x8 pa2, bf16x8 pa3) {
;   pv_one<0>(o[0], vb, pa0, pa1, pa2, pa3); pv_one<1>(o[1], vb, pa0, pa1, pa2, pa3); pv_one<2>(o[2], vb, pa0, pa1, pa2, pa3); pv_one<3>(o[3], vb, pa0, pa1, pa2, pa3);
; }
.Ldp_5:
	s_setprio 0
	s_add_i32 m0, s79, s30
	s_nop 0
	global_load_lds_dwordx4 v248, s[26:27]
	s_add_i32 m0, m0, 0x400
	s_nop 0
	global_load_lds_dwordx4 v249, s[26:27]
	s_add_i32 m0, s80, s30
	s_add_i32 m0, m0, 0xc000
	s_nop 0
	global_load_lds_dwordx4 v250, s[28:29]
	s_add_i32 m0, m0, 0x400
	s_nop 0
	global_load_lds_dwordx4 v251, s[28:29]
	s_add_u32 s26, s26, 0x90000
	s_addc_u32 s27, s27, 0
	s_add_u32 s28, s28, 0x90000
	s_addc_u32 s29, s29, 0
	v_add_u32_e32 v0, s80, v218
	ds_read_b64_tr_b16 v[82:83], v0 offset:0
	ds_read_b64_tr_b16 v[84:85], v0 offset:0x800
	ds_read_b64_tr_b16 v[86:87], v0 offset:0x1000
	ds_read_b64_tr_b16 v[88:89], v0 offset:0x1800
	ds_read_b64_tr_b16 v[90:91], v0 offset:0x2000
	ds_read_b64_tr_b16 v[92:93], v0 offset:0x2800
	ds_read_b64_tr_b16 v[94:95], v0 offset:0x3000
	ds_read_b64_tr_b16 v[96:97], v0 offset:0x3800
	s_waitcnt lgkmcnt(0)
	s_nop 0
	v_mfma_f32_32x32x16_bf16 v[50:65], v[66:69], v[82:85], v[50:65]
	ds_read_b64_tr_b16 v[82:83], v0 offset:0x200
	ds_read_b64_tr_b16 v[84:85], v0 offset:0xa00
	v_mfma_f32_32x32x16_bf16 v[50:65], v[70:73], v[86:89], v[50:65]
	ds_read_b64_tr_b16 v[86:87], v0 offset:0x1200
	ds_read_b64_tr_b16 v[88:89], v0 offset:0x1a00
	v_mfma_f32_32x32x16_bf16 v[50:65], v[74:77], v[90:93], v[50:65]
	ds_read_b64_tr_b16 v[90:91], v0 offset:0x2200
	ds_read_b64_tr_b16 v[92:93], v0 offset:0x2a00
	v_mfma_f32_32x32x16_bf16 v[50:65], v[78:81], v[94:97], v[50:65]
	ds_read_b64_tr_b16 v[94:95], v0 offset:0x3200
	ds_read_b64_tr_b16 v[96:97], v0 offset:0x3a00
	s_waitcnt lgkmcnt(0)
	v_mfma_f32_32x32x16_bf16 v[34:49], v[66:69], v[82:85], v[34:49]
	ds_read_b64_tr_b16 v[82:83], v0 offset:0x400
	ds_read_b64_tr_b16 v[84:85], v0 offset:0xc00
	v_mfma_f32_32x32x16_bf16 v[34:49], v[70:73], v[86:89], v[34:49]
	ds_read_b64_tr_b16 v[86:87], v0 offset:0x1400
	ds_read_b64_tr_b16 v[88:89], v0 offset:0x1c00
	v_mfma_f32_32x32x16_bf16 v[34:49], v[74:77], v[90:93], v[34:49]
	ds_read_b64_tr_b16 v[90:91], v0 offset:0x2400
	ds_read_b64_tr_b16 v[92:93], v0 offset:0x2c00
	v_mfma_f32_32x32x16_bf16 v[34:49], v[78:81], v[94:97], v[34:49]
	ds_read_b64_tr_b16 v[94:95], v0 offset:0x3400
	ds_read_b64_tr_b16 v[96:97], v0 offset:0x3c00
	s_waitcnt lgkmcnt(0)
	v_mfma_f32_32x32x16_bf16 v[18:33], v[66:69], v[82:85], v[18:33]
	ds_read_b64_tr_b16 v[82:83], v0 offset:0x600
	ds_read_b64_tr_b16 v[84:85], v0 offset:0xe00
	v_mfma_f32_32x32x16_bf16 v[18:33], v[70:73], v[86:89], v[18:33]
	ds_read_b64_tr_b16 v[86:87], v0 offset:0x1600
	ds_read_b64_tr_b16 v[88:89], v0 offset:0x1e00
	v_mfma_f32_32x32x16_bf16 v[18:33], v[74:77], v[90:93], v[18:33]
	ds_read_b64_tr_b16 v[90:91], v0 offset:0x2600
	ds_read_b64_tr_b16 v[92:93], v0 offset:0x2e00
	v_mfma_f32_32x32x16_bf16 v[18:33], v[78:81], v[94:97], v[18:33]
	ds_read_b64_tr_b16 v[94:95], v0 offset:0x3600
	ds_read_b64_tr_b16 v[96:97], v0 offset:0x3e00
	s_waitcnt lgkmcnt(0)
	v_mfma_f32_32x32x16_bf16 v[2:17], v[66:69], v[82:85], v[2:17]
	s_cmp_gt_i32 s95, s22
	s_cselect_b64 s[64:65], -1, 0
	s_cmp_lt_i32 s15, s22
	s_cselect_b64 vcc, -1, 0
	v_mov_b32_e32 v229, v160
	v_mfma_f32_32x32x16_bf16 v[2:17], v[70:73], v[86:89], v[2:17]
	v_mfma_f32_32x32x16_bf16 v[2:17], v[74:77], v[90:93], v[2:17]
	v_mfma_f32_32x32x16_bf16 v[2:17], v[78:81], v[94:97], v[2:17]
	s_setprio 1
	s_and_saveexec_b64 s[66:67], vcc
	s_cbranch_execz .LBB0_136
	s_cmp_gt_i32 s91, s23
	s_cselect_b64 vcc, -1, 0
	s_mov_b64 s[70:71], -1
	s_and_saveexec_b64 s[68:69], vcc
	s_cbranch_execz .LBB0_135
	v_add_u32_e32 v227, s77, v222
	v_add_u32_e32 v66, 64, v227
	v_add_u32_e32 v68, 0x41, v227
	v_add_u32_e32 v70, 0x42, v227
	v_add_u32_e32 v72, 0x43, v227
	v_med3_i32 v67, v66, s39, v198
	v_med3_i32 v66, v66, s33, v199
	v_med3_i32 v69, v68, s39, v198
	v_med3_i32 v68, v68, s33, v199
	v_med3_i32 v71, v70, s39, v198
	v_med3_i32 v70, v70, s33, v199
	v_med3_i32 v73, v72, s39, v198
	v_med3_i32 v72, v72, s33, v199
	v_lshl_add_u32 v67, v67, 2, s76
	v_lshl_add_u32 v66, v66, 2, s76
	v_lshl_add_u32 v69, v69, 2, s76
	v_lshl_add_u32 v68, v68, 2, s76
	v_lshl_add_u32 v70, v70, 2, s76
	v_lshl_add_u32 v72, v72, 2, s76
	v_lshl_add_u32 v71, v71, 2, s76
	v_lshl_add_u32 v73, v73, 2, s76
	ds_read_b32 v194, v67 offset:516
	ds_read_b32 v66, v66 offset:644
	ds_read_b32 v195, v69 offset:516
	ds_read_b32 v67, v68 offset:644
	ds_read_b32 v229, v71 offset:516
	ds_read_b32 v68, v70 offset:644
	ds_read_b32 v230, v73 offset:516
	ds_read_b32 v69, v72 offset:644
	v_add_u32_e32 v70, 0x48, v227
	v_add_u32_e32 v72, 0x49, v227
	v_add_u32_e32 v74, 0x4a, v227
	v_add_u32_e32 v76, 0x4b, v227
	v_med3_i32 v71, v70, s39, v198
	v_med3_i32 v70, v70, s33, v199
	v_med3_i32 v73, v72, s39, v198
	v_med3_i32 v72, v72, s33, v199
	v_med3_i32 v75, v74, s39, v198
	v_med3_i32 v74, v74, s33, v199
	v_med3_i32 v77, v76, s39, v198
	v_med3_i32 v76, v76, s33, v199
	v_lshl_add_u32 v71, v71, 2, s76
	v_lshl_add_u32 v70, v70, 2, s76
	v_lshl_add_u32 v73, v73, 2, s76
	v_lshl_add_u32 v72, v72, 2, s76
	v_lshl_add_u32 v74, v74, 2, s76
	v_lshl_add_u32 v76, v76, 2, s76
	v_lshl_add_u32 v75, v75, 2, s76
	v_lshl_add_u32 v77, v77, 2, s76
	ds_read_b32 v231, v71 offset:516
	ds_read_b32 v70, v70 offset:644
	ds_read_b32 v232, v73 offset:516
	ds_read_b32 v71, v72 offset:644
	ds_read_b32 v233, v75 offset:516
	ds_read_b32 v72, v74 offset:644
	ds_read_b32 v234, v77 offset:516
	ds_read_b32 v73, v76 offset:644
	v_add_u32_e32 v74, 0x50, v227
	v_add_u32_e32 v76, 0x51, v227
	v_add_u32_e32 v78, 0x52, v227
	v_add_u32_e32 v80, 0x53, v227
	v_med3_i32 v75, v74, s39, v198
	v_med3_i32 v74, v74, s33, v199
	v_med3_i32 v77, v76, s39, v198
	v_med3_i32 v76, v76, s33, v199
	v_med3_i32 v79, v78, s39, v198
	v_med3_i32 v78, v78, s33, v199
	v_med3_i32 v81, v80, s39, v198
	v_med3_i32 v80, v80, s33, v199
	v_lshl_add_u32 v75, v75, 2, s76
	v_lshl_add_u32 v74, v74, 2, s76
	v_lshl_add_u32 v77, v77, 2, s76
	v_lshl_add_u32 v76, v76, 2, s76
	v_lshl_add_u32 v78, v78, 2, s76
	v_lshl_add_u32 v80, v80, 2, s76
	v_lshl_add_u32 v79, v79, 2, s76
	v_lshl_add_u32 v81, v81, 2, s76
	ds_read_b32 v235, v75 offset:516
	ds_read_b32 v74, v74 offset:644
	ds_read_b32 v236, v77 offset:516
	ds_read_b32 v75, v76 offset:644
	ds_read_b32 v237, v79 offset:516
	ds_read_b32 v76, v78 offset:644
	ds_read_b32 v238, v81 offset:516
	ds_read_b32 v77, v80 offset:644
	v_add_u32_e32 v78, 0x58, v227
	v_add_u32_e32 v80, 0x59, v227
	v_add_u32_e32 v82, 0x5a, v227
	v_med3_i32 v79, v78, s39, v198
	v_med3_i32 v78, v78, s33, v199
	v_med3_i32 v81, v80, s39, v198
	v_med3_i32 v80, v80, s33, v199
	v_med3_i32 v83, v82, s39, v198
	v_med3_i32 v82, v82, s33, v199
	v_add_u32_e32 v84, 0x5b, v227
	s_waitcnt lgkmcnt(14)
; template <int MODE>
; __device__ __forceinline__ void partialSM(f32x16& p0, f32x16& p1, float& m_reg, float& mn, float& alpha, int relh, int relw_min, int relw_max, const float* lut) {
;     ...
;       for (int r = 0; r < 16; ++r) { const int i0 = relh + (r & 3) + 8 * (r >> 2);
;         const int a0 = min(max(i0, -129), 129) + 129, a1 = min(max(i0 + 32, -129), 129) + 129;
;         p0[r] = fmaf(p0[r], C, lut[a0]); p1[r] = fmaf(p1[r], C, lut[a1]); }
;     } else {
; #pragma unroll
;       for (int r = 0; r < 16; ++r) { p0[r] = fmaf(p0[r], C, cfar); p1[r] = fmaf(p1[r], C, cfar); }
;     }
;     float pmax = p0[0];
; #pragma unroll
;     for (int r = 1; r < 16; ++r) pmax = fmaxf(pmax, p0[r]);
; #pragma unroll
;     for (int r = 0; r < 16; ++r) pmax = fmaxf(pmax, p1[r]);
;     { auto rr = __builtin_amdgcn_permlane32_swap(__float_as_uint(pmax), __float_as_uint(pmax), false, false);
;       pmax = fmaxf(__uint_as_float(rr[0]), __uint_as_float(rr[1])); }
;     if (__builtin_expect(__all(pmax - m_reg <= THR2), 1)) { mn = m_reg; alpha = 1.f; }
;     else { mn = fmaxf(m_reg, pmax); alpha = __builtin_amdgcn_exp2f(m_reg - mn); m_reg = mn; }
; #pragma unroll
;     for (int r = 0; r < 16; ++r) p0[r] = __builtin_amdgcn_exp2f(p0[r] - mn);
; #pragma unroll
;     for (int r = 0; r < 16; ++r) p1[r] = p1[r] - mn;
	v_fmac_f32_e32 v194, 0x3e38aa3b, v114
	v_fmac_f32_e32 v195, 0x3e38aa3b, v115
	v_lshl_add_u32 v79, v79, 2, s76
	v_lshl_add_u32 v78, v78, 2, s76
	v_lshl_add_u32 v81, v81, 2, s76
	v_lshl_add_u32 v80, v80, 2, s76
	v_lshl_add_u32 v82, v82, 2, s76
	v_med3_i32 v85, v84, s39, v198
	v_med3_i32 v84, v84, s33, v199
	v_fmac_f32_e32 v229, 0x3e38aa3b, v116
	v_fmac_f32_e32 v230, 0x3e38aa3b, v117
	v_lshl_add_u32 v83, v83, 2, s76
	v_lshl_add_u32 v85, v85, 2, s76
	v_lshl_add_u32 v84, v84, 2, s76
	ds_read_b32 v239, v79 offset:516
	ds_read_b32 v78, v78 offset:644
	ds_read_b32 v240, v81 offset:516
	ds_read_b32 v79, v80 offset:644
	ds_read_b32 v241, v83 offset:516
	ds_read_b32 v80, v82 offset:644
	ds_read_b32 v242, v85 offset:516
	ds_read_b32 v81, v84 offset:644
	v_max_f32_e32 v82, v194, v195
	v_fmac_f32_e32 v231, 0x3e38aa3b, v118
	s_waitcnt lgkmcnt(14)
	v_fmac_f32_e32 v232, 0x3e38aa3b, v119
	v_max3_f32 v82, v82, v229, v230
	v_fmac_f32_e32 v233, 0x3e38aa3b, v120
	v_fmac_f32_e32 v234, 0x3e38aa3b, v121
	v_max3_f32 v82, v82, v231, v232
	v_fmac_f32_e32 v235, 0x3e38aa3b, v122
	s_waitcnt lgkmcnt(13)
	v_fmac_f32_e32 v236, 0x3e38aa3b, v123
	v_max3_f32 v82, v82, v233, v234
	s_waitcnt lgkmcnt(11)
	v_fmac_f32_e32 v237, 0x3e38aa3b, v124
	s_waitcnt lgkmcnt(9)
	v_fmac_f32_e32 v238, 0x3e38aa3b, v125
	v_max3_f32 v82, v82, v235, v236
	s_waitcnt lgkmcnt(7)
	v_fmac_f32_e32 v239, 0x3e38aa3b, v126
	s_waitcnt lgkmcnt(5)
	v_fmac_f32_e32 v240, 0x3e38aa3b, v127
	v_max3_f32 v82, v82, v237, v238
	s_waitcnt lgkmcnt(3)
	v_fmac_f32_e32 v241, 0x3e38aa3b, v128
	s_waitcnt lgkmcnt(1)
	v_fmac_f32_e32 v242, 0x3e38aa3b, v129
	v_max3_f32 v82, v82, v239, v240
	v_max3_f32 v84, v82, v241, v242
	v_pk_fma_f32 v[82:83], v[98:99], s[48:49], v[66:67] op_sel_hi:[1,0,1]
	v_pk_fma_f32 v[86:87], v[102:103], s[48:49], v[70:71] op_sel_hi:[1,0,1]
	v_max3_f32 v66, v84, v82, v83
	v_pk_fma_f32 v[84:85], v[100:101], s[48:49], v[68:69] op_sel_hi:[1,0,1]
	v_pk_fma_f32 v[88:89], v[104:105], s[48:49], v[72:73] op_sel_hi:[1,0,1]
	v_max3_f32 v66, v66, v84, v85
	v_max3_f32 v66, v66, v86, v87
	v_max3_f32 v66, v66, v88, v89
	v_pk_fma_f32 v[90:91], v[106:107], s[48:49], v[74:75] op_sel_hi:[1,0,1]
	v_pk_fma_f32 v[92:93], v[108:109], s[48:49], v[76:77] op_sel_hi:[1,0,1]
	v_max3_f32 v66, v66, v90, v91
	v_max3_f32 v66, v66, v92, v93
	v_pk_fma_f32 v[94:95], v[110:111], s[48:49], v[78:79] op_sel_hi:[1,0,1]
	s_waitcnt lgkmcnt(0)
	v_pk_fma_f32 v[96:97], v[112:113], s[48:49], v[80:81] op_sel_hi:[1,0,1]
	v_max3_f32 v66, v66, v94, v95
	v_max3_f32 v66, v66, v96, v97
	v_mov_b32_e32 v67, v66
	s_nop 1
	v_permlane32_swap_b32_e32 v66, v67
	v_max_f32_e32 v66, v66, v67
	v_sub_f32_e32 v67, v66, v219
	v_cmp_ge_f32_e32 vcc, s94, v67
	v_max_f32_e32 v66, v219, v66
	v_sub_f32_e32 v67, v219, v66
	v_exp_f32_e32 v67, v67
	s_cmp_eq_u64 vcc, exec
	s_cselect_b64 vcc, -1, 0
	v_cndmask_b32_e32 v228, v66, v219, vcc
	v_cndmask_b32_e64 v226, v67, 1.0, vcc
	v_sub_f32_e32 v66, v194, v228
	v_sub_f32_e32 v67, v195, v228
	v_sub_f32_e32 v68, v229, v228
	v_sub_f32_e32 v69, v230, v228
	v_sub_f32_e32 v70, v231, v228
	v_sub_f32_e32 v71, v232, v228
	v_sub_f32_e32 v72, v233, v228
	v_sub_f32_e32 v73, v234, v228
	v_sub_f32_e32 v74, v235, v228
	v_sub_f32_e32 v75, v236, v228
	v_sub_f32_e32 v76, v237, v228
	v_sub_f32_e32 v77, v238, v228
	v_sub_f32_e32 v78, v239, v228
	v_sub_f32_e32 v79, v240, v228
	v_sub_f32_e32 v80, v241, v228
	v_sub_f32_e32 v81, v242, v228
	v_exp_f32_e32 v66, v66
	v_exp_f32_e32 v67, v67
	v_exp_f32_e32 v68, v68
	v_exp_f32_e32 v69, v69
	v_exp_f32_e32 v70, v70
	v_exp_f32_e32 v71, v71
	v_exp_f32_e32 v72, v72
	v_exp_f32_e32 v73, v73
	v_exp_f32_e32 v74, v74
	v_exp_f32_e32 v75, v75
	v_exp_f32_e32 v76, v76
	v_exp_f32_e32 v77, v77
	v_exp_f32_e32 v78, v78
	v_exp_f32_e32 v79, v79
	v_exp_f32_e32 v80, v80
	v_exp_f32_e32 v81, v81
	v_sub_f32_e32 v97, v97, v228
	v_sub_f32_e32 v96, v96, v228
	v_sub_f32_e32 v95, v95, v228
	v_sub_f32_e32 v94, v94, v228
	v_sub_f32_e32 v93, v93, v228
	v_sub_f32_e32 v92, v92, v228
	v_sub_f32_e32 v91, v91, v228
	v_sub_f32_e32 v90, v90, v228
	v_sub_f32_e32 v89, v89, v228
	v_sub_f32_e32 v88, v88, v228
	v_sub_f32_e32 v87, v87, v228
	v_sub_f32_e32 v86, v86, v228
	v_sub_f32_e32 v85, v85, v228
	v_sub_f32_e32 v84, v84, v228
	v_sub_f32_e32 v83, v83, v228
	v_sub_f32_e32 v82, v82, v228
	s_xor_b64 s[70:71], exec, -1

; #define SBAR() __builtin_amdgcn_sched_barrier(0)
; template <int MODE>
; __device__ __forceinline__ void partialSM(f32x16& p0, f32x16& p1, float& m_reg, float& mn, float& alpha, int relh, int relw_min, int relw_max, const float* lut) {
;     ...
;     if (nearT) {
; #pragma unroll
;       for (int r = 0; r < 16; ++r) { const int i0 = relh + (r & 3) + 8 * (r >> 2);
;         const int a0 = min(max(i0, -129), 129) + 129, a1 = min(max(i0 + 32, -129), 129) + 129;
;         p0[r] = fmaf(p0[r], C, lut[a0]); p1[r] = fmaf(p1[r], C, lut[a1]); }
;     } else {
; #pragma unroll
;       for (int r = 0; r < 16; ++r) { p0[r] = fmaf(p0[r], C, cfar); p1[r] = fmaf(p1[r], C, cfar); }
; __device__ __forceinline__ int v_st(int k, int c) { const int kk = (k & ~0xC) | ((k & 4) << 1) | ((k & 8) >> 1); return ((kk >> 3) * 4 + (c >> 5)) * 512 + ((kk & 7) * 32 + (c & 31)) * 2; }
; __device__ __forceinline__ int v_rd_base(int lane) { return ((lane & 3) << 3) | (((lane >> 2) & 3) << 6) | (((lane >> 4) & 1) << 5) | (((lane >> 5) & 1) << 8); }
; template <int OFF> __device__ __forceinline__ s16x4 tr_read(int vb) {
;   s16x4 r; asm volatile("ds_read_b64_tr_b16 %0, %1 offset:%2" : "=&v"(r) : "v"(vb), "i"(OFF) : "memory"); return r;
; }
; template <int D0> __device__ __forceinline__ void pv_one(f32x16& od, int vb, bf16x8 pa0, bf16x8 pa1, bf16x8 pa2, bf16x8 pa3) {
;   const s16x4 l0 = tr_read<v_rd_off(D0, 0, 0)>(vb), h0 = tr_read<v_rd_off(D0, 0, 1)>(vb), l1 = tr_read<v_rd_off(D0, 1, 0)>(vb), h1 = tr_read<v_rd_off(D0, 1, 1)>(vb);
;   const s16x4 l2 = tr_read<v_rd_off(D0, 2, 0)>(vb), h2 = tr_read<v_rd_off(D0, 2, 1)>(vb), l3 = tr_read<v_rd_off(D0, 3, 0)>(vb), h3 = tr_read<v_rd_off(D0, 3, 1)>(vb);
;   asm volatile("s_waitcnt lgkmcnt(0)" ::: "memory"); SBAR();
;     ...
;   od = __builtin_amdgcn_mfma_f32_32x32x16_bf16(pa0, PK(l0, h0), od, 0, 0, 0);
;   od = __builtin_amdgcn_mfma_f32_32x32x16_bf16(pa1, PK(l1, h1), od, 0, 0, 0);
;   od = __builtin_amdgcn_mfma_f32_32x32x16_bf16(pa2, PK(l2, h2), od, 0, 0, 0);
;   od = __builtin_amdgcn_mfma_f32_32x32x16_bf16(pa3, PK(l3, h3), od, 0, 0, 0);
;     ...
; }
; __device__ __forceinline__ void pv_d0(f32x16* o, int vb, bf16x8 pa0, bf16x8 pa1, bf16x8 pa2, bf16x8 pa3) {
;   pv_one<0>(o[0], vb, pa0, pa1, pa2, pa3); pv_one<1>(o[1], vb, pa0, pa1, pa2, pa3); pv_one<2>(o[2], vb, pa0, pa1, pa2, pa3); pv_one<3>(o[3], vb, pa0, pa1, pa2, pa3);
; }
.Ldp_3:
	s_setprio 0
	s_add_i32 m0, s80, s30
	s_nop 0
	global_load_lds_dwordx4 v248, s[26:27]
	s_add_i32 m0, m0, 0x400
	s_nop 0
	global_load_lds_dwordx4 v249, s[26:27]
	s_add_i32 m0, s82, s30
	s_add_i32 m0, m0, 0xc000
	s_nop 0
	global_load_lds_dwordx4 v250, s[28:29]
	s_add_i32 m0, m0, 0x400
	s_nop 0
	global_load_lds_dwordx4 v251, s[28:29]
	s_add_u32 s26, s26, 0x90000
	s_addc_u32 s27, s27, 0
	s_add_u32 s28, s28, 0x90000
	s_addc_u32 s29, s29, 0
.LBB0_144:
	v_add_u32_e32 v194, s82, v218
	ds_read_b64_tr_b16 v[82:83], v194 offset:0
	ds_read_b64_tr_b16 v[84:85], v194 offset:0x800
	ds_read_b64_tr_b16 v[86:87], v194 offset:0x1000
	ds_read_b64_tr_b16 v[88:89], v194 offset:0x1800
	ds_read_b64_tr_b16 v[90:91], v194 offset:0x2000
	ds_read_b64_tr_b16 v[92:93], v194 offset:0x2800
	ds_read_b64_tr_b16 v[94:95], v194 offset:0x3000
	ds_read_b64_tr_b16 v[96:97], v194 offset:0x3800
	s_waitcnt lgkmcnt(0)
	s_nop 0
	v_mfma_f32_32x32x16_bf16 v[50:65], v[66:69], v[82:85], v[50:65]
	ds_read_b64_tr_b16 v[82:83], v194 offset:0x200
	ds_read_b64_tr_b16 v[84:85], v194 offset:0xa00
	v_mfma_f32_32x32x16_bf16 v[50:65], v[70:73], v[86:89], v[50:65]
	ds_read_b64_tr_b16 v[86:87], v194 offset:0x1200
	ds_read_b64_tr_b16 v[88:89], v194 offset:0x1a00
	v_mfma_f32_32x32x16_bf16 v[50:65], v[74:77], v[90:93], v[50:65]
	ds_read_b64_tr_b16 v[90:91], v194 offset:0x2200
	ds_read_b64_tr_b16 v[92:93], v194 offset:0x2a00
	v_mfma_f32_32x32x16_bf16 v[50:65], v[78:81], v[94:97], v[50:65]
	ds_read_b64_tr_b16 v[94:95], v194 offset:0x3200
	ds_read_b64_tr_b16 v[96:97], v194 offset:0x3a00
	s_waitcnt lgkmcnt(0)
	v_mfma_f32_32x32x16_bf16 v[34:49], v[66:69], v[82:85], v[34:49]
	ds_read_b64_tr_b16 v[82:83], v194 offset:0x400
	ds_read_b64_tr_b16 v[84:85], v194 offset:0xc00
	v_mfma_f32_32x32x16_bf16 v[34:49], v[70:73], v[86:89], v[34:49]
	ds_read_b64_tr_b16 v[86:87], v194 offset:0x1400
	ds_read_b64_tr_b16 v[88:89], v194 offset:0x1c00
	v_mfma_f32_32x32x16_bf16 v[34:49], v[74:77], v[90:93], v[34:49]
	ds_read_b64_tr_b16 v[90:91], v194 offset:0x2400
	ds_read_b64_tr_b16 v[92:93], v194 offset:0x2c00
	v_mfma_f32_32x32x16_bf16 v[34:49], v[78:81], v[94:97], v[34:49]
	ds_read_b64_tr_b16 v[94:95], v194 offset:0x3400
	ds_read_b64_tr_b16 v[96:97], v194 offset:0x3c00
	s_waitcnt lgkmcnt(0)
	v_mfma_f32_32x32x16_bf16 v[18:33], v[66:69], v[82:85], v[18:33]
	ds_read_b64_tr_b16 v[82:83], v194 offset:0x600
	ds_read_b64_tr_b16 v[84:85], v194 offset:0xe00
	v_mfma_f32_32x32x16_bf16 v[18:33], v[70:73], v[86:89], v[18:33]
	ds_read_b64_tr_b16 v[86:87], v194 offset:0x1600
	ds_read_b64_tr_b16 v[88:89], v194 offset:0x1e00
	v_mfma_f32_32x32x16_bf16 v[18:33], v[74:77], v[90:93], v[18:33]
	ds_read_b64_tr_b16 v[90:91], v194 offset:0x2600
	ds_read_b64_tr_b16 v[92:93], v194 offset:0x2e00
	v_mfma_f32_32x32x16_bf16 v[18:33], v[78:81], v[94:97], v[18:33]
	ds_read_b64_tr_b16 v[94:95], v194 offset:0x3600
	ds_read_b64_tr_b16 v[96:97], v194 offset:0x3e00
	s_waitcnt lgkmcnt(0)
	v_mfma_f32_32x32x16_bf16 v[2:17], v[66:69], v[82:85], v[2:17]
	s_cmp_gt_i32 s95, s24
	s_cselect_b64 s[66:67], -1, 0
	s_cmp_lt_i32 s15, s24
	s_cselect_b64 vcc, -1, 0
	v_mov_b32_e32 v231, v160
	v_mfma_f32_32x32x16_bf16 v[2:17], v[70:73], v[86:89], v[2:17]
	v_mfma_f32_32x32x16_bf16 v[2:17], v[74:77], v[90:93], v[2:17]
	v_mfma_f32_32x32x16_bf16 v[2:17], v[78:81], v[94:97], v[2:17]
	s_setprio 1
	s_and_saveexec_b64 s[68:69], vcc
	s_cbranch_execz .LBB0_148
	s_cmp_gt_i32 s91, s25
	s_cselect_b64 vcc, -1, 0
	s_mov_b64 s[72:73], -1
	s_and_saveexec_b64 s[70:71], vcc
	s_cbranch_execz .LBB0_147
	v_add_u32_e32 v227, s77, v222
	v_add_u32_e32 v66, 0x80, v227
	v_add_u32_e32 v68, 0x81, v227
	v_add_u32_e32 v70, 0x82, v227
	v_add_u32_e32 v72, 0x83, v227
	v_med3_i32 v67, v66, s39, v198
	v_med3_i32 v66, v66, s33, v199
	v_med3_i32 v69, v68, s39, v198
	v_med3_i32 v68, v68, s33, v199
	v_med3_i32 v71, v70, s39, v198
	v_med3_i32 v70, v70, s33, v199
	v_med3_i32 v73, v72, s39, v198
	v_med3_i32 v72, v72, s33, v199
	v_lshl_add_u32 v67, v67, 2, s76
	v_lshl_add_u32 v66, v66, 2, s76
	v_lshl_add_u32 v69, v69, 2, s76
	v_lshl_add_u32 v68, v68, 2, s76
	v_lshl_add_u32 v70, v70, 2, s76
	v_lshl_add_u32 v72, v72, 2, s76
	v_lshl_add_u32 v71, v71, 2, s76
	v_lshl_add_u32 v73, v73, 2, s76
	ds_read_b32 v194, v67 offset:516
	ds_read_b32 v66, v66 offset:644
	ds_read_b32 v195, v69 offset:516
	ds_read_b32 v67, v68 offset:644
	ds_read_b32 v231, v71 offset:516
	ds_read_b32 v68, v70 offset:644
	ds_read_b32 v232, v73 offset:516
	ds_read_b32 v69, v72 offset:644
	v_add_u32_e32 v70, 0x88, v227
	v_add_u32_e32 v72, 0x89, v227
	v_add_u32_e32 v74, 0x8a, v227
	v_add_u32_e32 v76, 0x8b, v227
	v_med3_i32 v71, v70, s39, v198
	v_med3_i32 v70, v70, s33, v199
	v_med3_i32 v73, v72, s39, v198
	v_med3_i32 v72, v72, s33, v199
	v_med3_i32 v75, v74, s39, v198
	v_med3_i32 v74, v74, s33, v199
	v_med3_i32 v77, v76, s39, v198
	v_med3_i32 v76, v76, s33, v199
	v_lshl_add_u32 v71, v71, 2, s76
	v_lshl_add_u32 v70, v70, 2, s76
	v_lshl_add_u32 v73, v73, 2, s76
	v_lshl_add_u32 v72, v72, 2, s76
	v_lshl_add_u32 v74, v74, 2, s76
	v_lshl_add_u32 v76, v76, 2, s76
	v_lshl_add_u32 v75, v75, 2, s76
	v_lshl_add_u32 v77, v77, 2, s76
	ds_read_b32 v233, v71 offset:516
	ds_read_b32 v70, v70 offset:644
	ds_read_b32 v234, v73 offset:516
	ds_read_b32 v71, v72 offset:644
	ds_read_b32 v235, v75 offset:516
	ds_read_b32 v72, v74 offset:644
	ds_read_b32 v236, v77 offset:516
	ds_read_b32 v73, v76 offset:644
	v_add_u32_e32 v74, 0x90, v227
	v_add_u32_e32 v76, 0x91, v227
	v_add_u32_e32 v78, 0x92, v227
	v_add_u32_e32 v80, 0x93, v227
	v_med3_i32 v75, v74, s39, v198
	v_med3_i32 v74, v74, s33, v199
	v_med3_i32 v77, v76, s39, v198
	v_med3_i32 v76, v76, s33, v199
	v_med3_i32 v79, v78, s39, v198
	v_med3_i32 v78, v78, s33, v199
	v_med3_i32 v81, v80, s39, v198
	v_med3_i32 v80, v80, s33, v199
	v_lshl_add_u32 v75, v75, 2, s76
	v_lshl_add_u32 v74, v74, 2, s76
	v_lshl_add_u32 v77, v77, 2, s76
	v_lshl_add_u32 v76, v76, 2, s76
	v_lshl_add_u32 v78, v78, 2, s76
	v_lshl_add_u32 v80, v80, 2, s76
	v_lshl_add_u32 v79, v79, 2, s76
	v_lshl_add_u32 v81, v81, 2, s76
	ds_read_b32 v237, v75 offset:516
	ds_read_b32 v74, v74 offset:644
	ds_read_b32 v238, v77 offset:516
	ds_read_b32 v75, v76 offset:644
	ds_read_b32 v239, v79 offset:516
	ds_read_b32 v76, v78 offset:644
	ds_read_b32 v240, v81 offset:516
	ds_read_b32 v77, v80 offset:644
	v_add_u32_e32 v78, 0x98, v227
	v_add_u32_e32 v80, 0x99, v227
	v_add_u32_e32 v82, 0x9a, v227
	v_med3_i32 v79, v78, s39, v198
	v_med3_i32 v78, v78, s33, v199
	v_med3_i32 v81, v80, s39, v198
	v_med3_i32 v80, v80, s33, v199
	v_med3_i32 v83, v82, s39, v198
	v_med3_i32 v82, v82, s33, v199
	v_add_u32_e32 v84, 0x9b, v227
	s_waitcnt lgkmcnt(14)
; template <int MODE>
; __device__ __forceinline__ void partialSM(f32x16& p0, f32x16& p1, float& m_reg, float& mn, float& alpha, int relh, int relw_min, int relw_max, const float* lut) {
;     ...
;     if (nearT) {
; #pragma unroll
;       for (int r = 0; r < 16; ++r) { const int i0 = relh + (r & 3) + 8 * (r >> 2);
;         const int a0 = min(max(i0, -129), 129) + 129, a1 = min(max(i0 + 32, -129), 129) + 129;
;         p0[r] = fmaf(p0[r], C, lut[a0]); p1[r] = fmaf(p1[r], C, lut[a1]); }
;     } else {
; #pragma unroll
;       for (int r = 0; r < 16; ++r) { p0[r] = fmaf(p0[r], C, cfar); p1[r] = fmaf(p1[r], C, cfar); }
;     }
;     float pmax = p0[0];
; #pragma unroll
;     for (int r = 1; r < 16; ++r) pmax = fmaxf(pmax, p0[r]);
; #pragma unroll
;     for (int r = 0; r < 16; ++r) pmax = fmaxf(pmax, p1[r]);
;     { auto rr = __builtin_amdgcn_permlane32_swap(__float_as_uint(pmax), __float_as_uint(pmax), false, false);
;       pmax = fmaxf(__uint_as_float(rr[0]), __uint_as_float(rr[1])); }
;     if (__builtin_expect(__all(pmax - m_reg <= THR2), 1)) { mn = m_reg; alpha = 1.f; }
;     else { mn = fmaxf(m_reg, pmax); alpha = __builtin_amdgcn_exp2f(m_reg - mn); m_reg = mn; }
; #pragma unroll
;     for (int r = 0; r < 16; ++r) p0[r] = __builtin_amdgcn_exp2f(p0[r] - mn);
; #pragma unroll
;     for (int r = 0; r < 16; ++r) p1[r] = p1[r] - mn;
	v_fmac_f32_e32 v194, 0x3e38aa3b, v114
	v_fmac_f32_e32 v195, 0x3e38aa3b, v115
	v_lshl_add_u32 v79, v79, 2, s76
	v_lshl_add_u32 v78, v78, 2, s76
	v_lshl_add_u32 v81, v81, 2, s76
	v_lshl_add_u32 v80, v80, 2, s76
	v_lshl_add_u32 v82, v82, 2, s76
	v_med3_i32 v85, v84, s39, v198
	v_med3_i32 v84, v84, s33, v199
	v_fmac_f32_e32 v231, 0x3e38aa3b, v116
	v_fmac_f32_e32 v232, 0x3e38aa3b, v117
	v_lshl_add_u32 v83, v83, 2, s76
	v_lshl_add_u32 v85, v85, 2, s76
	v_lshl_add_u32 v84, v84, 2, s76
	ds_read_b32 v227, v79 offset:516
	ds_read_b32 v78, v78 offset:644
	ds_read_b32 v241, v81 offset:516
	ds_read_b32 v79, v80 offset:644
	ds_read_b32 v242, v83 offset:516
	ds_read_b32 v80, v82 offset:644
	ds_read_b32 v243, v85 offset:516
	ds_read_b32 v81, v84 offset:644
	v_max_f32_e32 v82, v194, v195
	v_fmac_f32_e32 v233, 0x3e38aa3b, v118
	s_waitcnt lgkmcnt(14)
	v_fmac_f32_e32 v234, 0x3e38aa3b, v119
	v_max3_f32 v82, v82, v231, v232
	v_fmac_f32_e32 v235, 0x3e38aa3b, v120
	v_fmac_f32_e32 v236, 0x3e38aa3b, v121
	v_max3_f32 v82, v82, v233, v234
	v_fmac_f32_e32 v237, 0x3e38aa3b, v122
	s_waitcnt lgkmcnt(13)
	v_fmac_f32_e32 v238, 0x3e38aa3b, v123
	v_max3_f32 v82, v82, v235, v236
	s_waitcnt lgkmcnt(11)
	v_fmac_f32_e32 v239, 0x3e38aa3b, v124
	s_waitcnt lgkmcnt(9)
	v_fmac_f32_e32 v240, 0x3e38aa3b, v125
	v_max3_f32 v82, v82, v237, v238
	s_waitcnt lgkmcnt(7)
	v_fmac_f32_e32 v227, 0x3e38aa3b, v126
	s_waitcnt lgkmcnt(5)
	v_fmac_f32_e32 v241, 0x3e38aa3b, v127
	v_max3_f32 v82, v82, v239, v240
	s_waitcnt lgkmcnt(3)
	v_fmac_f32_e32 v242, 0x3e38aa3b, v128
	s_waitcnt lgkmcnt(1)
	v_fmac_f32_e32 v243, 0x3e38aa3b, v129
	v_max3_f32 v82, v82, v227, v241
	v_max3_f32 v84, v82, v242, v243
	v_pk_fma_f32 v[82:83], v[98:99], s[48:49], v[66:67] op_sel_hi:[1,0,1]
	v_pk_fma_f32 v[86:87], v[102:103], s[48:49], v[70:71] op_sel_hi:[1,0,1]
	v_max3_f32 v66, v84, v82, v83
	v_pk_fma_f32 v[84:85], v[100:101], s[48:49], v[68:69] op_sel_hi:[1,0,1]
	v_pk_fma_f32 v[88:89], v[104:105], s[48:49], v[72:73] op_sel_hi:[1,0,1]
	v_max3_f32 v66, v66, v84, v85
	v_max3_f32 v66, v66, v86, v87
	v_max3_f32 v66, v66, v88, v89
	v_pk_fma_f32 v[90:91], v[106:107], s[48:49], v[74:75] op_sel_hi:[1,0,1]
	v_pk_fma_f32 v[92:93], v[108:109], s[48:49], v[76:77] op_sel_hi:[1,0,1]
	v_max3_f32 v66, v66, v90, v91
	v_max3_f32 v66, v66, v92, v93
	v_pk_fma_f32 v[94:95], v[110:111], s[48:49], v[78:79] op_sel_hi:[1,0,1]
	s_waitcnt lgkmcnt(0)
	v_pk_fma_f32 v[96:97], v[112:113], s[48:49], v[80:81] op_sel_hi:[1,0,1]
	v_max3_f32 v66, v66, v94, v95
	v_max3_f32 v66, v66, v96, v97
	v_mov_b32_e32 v67, v66
	s_nop 1
	v_permlane32_swap_b32_e32 v66, v67
	v_max_f32_e32 v66, v66, v67
	v_sub_f32_e32 v67, v66, v228
	v_cmp_ge_f32_e32 vcc, s94, v67
	v_max_f32_e32 v66, v228, v66
	v_sub_f32_e32 v67, v228, v66
	v_exp_f32_e32 v67, v67
	s_cmp_eq_u64 vcc, exec
	s_cselect_b64 vcc, -1, 0
	v_cndmask_b32_e32 v219, v66, v228, vcc
	v_cndmask_b32_e64 v225, v67, 1.0, vcc
	v_sub_f32_e32 v66, v194, v219
	v_sub_f32_e32 v67, v195, v219
	v_sub_f32_e32 v68, v231, v219
	v_sub_f32_e32 v69, v232, v219
	v_sub_f32_e32 v70, v233, v219
	v_sub_f32_e32 v71, v234, v219
	v_sub_f32_e32 v72, v235, v219
	v_sub_f32_e32 v73, v236, v219
	v_sub_f32_e32 v74, v237, v219
	v_sub_f32_e32 v75, v238, v219
	v_sub_f32_e32 v76, v239, v219
	v_sub_f32_e32 v77, v240, v219
	v_sub_f32_e32 v78, v227, v219
	v_sub_f32_e32 v79, v241, v219
	v_sub_f32_e32 v80, v242, v219
	v_sub_f32_e32 v81, v243, v219
	v_exp_f32_e32 v66, v66
	v_exp_f32_e32 v67, v67
	v_exp_f32_e32 v68, v68
	v_exp_f32_e32 v69, v69
	v_exp_f32_e32 v70, v70
	v_exp_f32_e32 v71, v71
	v_exp_f32_e32 v72, v72
	v_exp_f32_e32 v73, v73
	v_exp_f32_e32 v74, v74
	v_exp_f32_e32 v75, v75
	v_exp_f32_e32 v76, v76
	v_exp_f32_e32 v77, v77
	v_exp_f32_e32 v78, v78
	v_exp_f32_e32 v79, v79
	v_exp_f32_e32 v80, v80
	v_exp_f32_e32 v81, v81
	v_sub_f32_e32 v97, v97, v219
	v_sub_f32_e32 v96, v96, v219
	v_sub_f32_e32 v95, v95, v219
	v_sub_f32_e32 v94, v94, v219
	v_sub_f32_e32 v93, v93, v219
	v_sub_f32_e32 v92, v92, v219
	v_sub_f32_e32 v91, v91, v219
	v_sub_f32_e32 v90, v90, v219
	v_sub_f32_e32 v89, v89, v219
	v_sub_f32_e32 v88, v88, v219
	v_sub_f32_e32 v87, v87, v219
	v_sub_f32_e32 v86, v86, v219
	v_sub_f32_e32 v85, v85, v219
	v_sub_f32_e32 v84, v84, v219
	v_sub_f32_e32 v83, v83, v219
	v_sub_f32_e32 v82, v82, v219
	s_xor_b64 s[72:73], exec, -1

; template <int MODE>
; __device__ __forceinline__ void attn_body(const bf16_t* __restrict__ Qb, const bf16_t* __restrict__ Kh, const bf16_t* __restrict__ Vh, int NT, int krel0,
;                                           char* lds, const float* __restrict__ lutg, const AttnEpi& E) {
;     ...
;   for (int j = 1; j + 1 < NT; j += 2) {
;     __syncthreads();
.LBB0_156:
	s_setprio 0
	s_cmp_lt_u32 s31, 4
	s_cbranch_scc0 .Ldp_2
	s_waitcnt vmcnt(0) lgkmcnt(0)
	s_barrier

; #define SBAR() __builtin_amdgcn_sched_barrier(0)
; template <int MODE>
; __device__ __forceinline__ void partialSM(f32x16& p0, f32x16& p1, float& m_reg, float& mn, float& alpha, int relh, int relw_min, int relw_max, const float* lut) {
;     ...
;     if (nearT) {
; #pragma unroll
;       for (int r = 0; r < 16; ++r) { const int i0 = relh + (r & 3) + 8 * (r >> 2);
;         const int a0 = min(max(i0, -129), 129) + 129, a1 = min(max(i0 + 32, -129), 129) + 129;
;         p0[r] = fmaf(p0[r], C, lut[a0]); p1[r] = fmaf(p1[r], C, lut[a1]); }
; template <int OFF> __device__ __forceinline__ s16x4 tr_read(int vb) {
;   s16x4 r; asm volatile("ds_read_b64_tr_b16 %0, %1 offset:%2" : "=&v"(r) : "v"(vb), "i"(OFF) : "memory"); return r;
; }
; template <int D0> __device__ __forceinline__ void pv_one(f32x16& od, int vb, bf16x8 pa0, bf16x8 pa1, bf16x8 pa2, bf16x8 pa3) {
;   const s16x4 l0 = tr_read<v_rd_off(D0, 0, 0)>(vb), h0 = tr_read<v_rd_off(D0, 0, 1)>(vb), l1 = tr_read<v_rd_off(D0, 1, 0)>(vb), h1 = tr_read<v_rd_off(D0, 1, 1)>(vb);
;   const s16x4 l2 = tr_read<v_rd_off(D0, 2, 0)>(vb), h2 = tr_read<v_rd_off(D0, 2, 1)>(vb), l3 = tr_read<v_rd_off(D0, 3, 0)>(vb), h3 = tr_read<v_rd_off(D0, 3, 1)>(vb);
;   asm volatile("s_waitcnt lgkmcnt(0)" ::: "memory"); SBAR();
;     ...
;   od = __builtin_amdgcn_mfma_f32_32x32x16_bf16(pa0, PK(l0, h0), od, 0, 0, 0);
;   od = __builtin_amdgcn_mfma_f32_32x32x16_bf16(pa1, PK(l1, h1), od, 0, 0, 0);
;   od = __builtin_amdgcn_mfma_f32_32x32x16_bf16(pa2, PK(l2, h2), od, 0, 0, 0);
;   od = __builtin_amdgcn_mfma_f32_32x32x16_bf16(pa3, PK(l3, h3), od, 0, 0, 0);
;     ...
; }
; __device__ __forceinline__ void pv_d0(f32x16* o, int vb, bf16x8 pa0, bf16x8 pa1, bf16x8 pa2, bf16x8 pa3) {
;   pv_one<0>(o[0], vb, pa0, pa1, pa2, pa3); pv_one<1>(o[1], vb, pa0, pa1, pa2, pa3); pv_one<2>(o[2], vb, pa0, pa1, pa2, pa3); pv_one<3>(o[3], vb, pa0, pa1, pa2, pa3);
.Ldp_11:
	s_setprio 0
	s_add_i32 m0, s2, s30
	s_nop 0
	global_load_lds_dwordx4 v248, s[26:27]
	s_add_i32 m0, m0, 0x400
	s_nop 0
	global_load_lds_dwordx4 v249, s[26:27]
	s_add_i32 m0, s66, s30
	s_add_i32 m0, m0, 0xc000
	s_nop 0
	global_load_lds_dwordx4 v250, s[28:29]
	s_add_i32 m0, m0, 0x400
	s_nop 0
	global_load_lds_dwordx4 v251, s[28:29]
	s_add_u32 s26, s26, 0x90000
	s_addc_u32 s27, s27, 0
	s_add_u32 s28, s28, 0x90000
	s_addc_u32 s29, s29, 0
	v_add_u32_e32 v0, s66, v221
	ds_read_b64_tr_b16 v[82:83], v0 offset:0
	ds_read_b64_tr_b16 v[84:85], v0 offset:0x800
	ds_read_b64_tr_b16 v[86:87], v0 offset:0x1000
	ds_read_b64_tr_b16 v[88:89], v0 offset:0x1800
	ds_read_b64_tr_b16 v[90:91], v0 offset:0x2000
	ds_read_b64_tr_b16 v[92:93], v0 offset:0x2800
	ds_read_b64_tr_b16 v[94:95], v0 offset:0x3000
	ds_read_b64_tr_b16 v[96:97], v0 offset:0x3800
	s_waitcnt lgkmcnt(0)
	s_nop 0
	v_mfma_f32_32x32x16_bf16 v[50:65], v[66:69], v[82:85], v[50:65]
	ds_read_b64_tr_b16 v[82:83], v0 offset:0x200
	ds_read_b64_tr_b16 v[84:85], v0 offset:0xa00
	v_mfma_f32_32x32x16_bf16 v[50:65], v[70:73], v[86:89], v[50:65]
	ds_read_b64_tr_b16 v[86:87], v0 offset:0x1200
	ds_read_b64_tr_b16 v[88:89], v0 offset:0x1a00
	v_mfma_f32_32x32x16_bf16 v[50:65], v[74:77], v[90:93], v[50:65]
	ds_read_b64_tr_b16 v[90:91], v0 offset:0x2200
	ds_read_b64_tr_b16 v[92:93], v0 offset:0x2a00
	v_mfma_f32_32x32x16_bf16 v[50:65], v[78:81], v[94:97], v[50:65]
	ds_read_b64_tr_b16 v[94:95], v0 offset:0x3200
	ds_read_b64_tr_b16 v[96:97], v0 offset:0x3a00
	s_waitcnt lgkmcnt(0)
	v_mfma_f32_32x32x16_bf16 v[34:49], v[66:69], v[82:85], v[34:49]
	ds_read_b64_tr_b16 v[82:83], v0 offset:0x400
	ds_read_b64_tr_b16 v[84:85], v0 offset:0xc00
	v_mfma_f32_32x32x16_bf16 v[34:49], v[70:73], v[86:89], v[34:49]
	ds_read_b64_tr_b16 v[86:87], v0 offset:0x1400
	ds_read_b64_tr_b16 v[88:89], v0 offset:0x1c00
	v_mfma_f32_32x32x16_bf16 v[34:49], v[74:77], v[90:93], v[34:49]
	ds_read_b64_tr_b16 v[90:91], v0 offset:0x2400
	ds_read_b64_tr_b16 v[92:93], v0 offset:0x2c00
	v_mfma_f32_32x32x16_bf16 v[34:49], v[78:81], v[94:97], v[34:49]
	ds_read_b64_tr_b16 v[94:95], v0 offset:0x3400
	ds_read_b64_tr_b16 v[96:97], v0 offset:0x3c00
	s_waitcnt lgkmcnt(0)
	v_mfma_f32_32x32x16_bf16 v[18:33], v[66:69], v[82:85], v[18:33]
	ds_read_b64_tr_b16 v[82:83], v0 offset:0x600
	ds_read_b64_tr_b16 v[84:85], v0 offset:0xe00
	v_mfma_f32_32x32x16_bf16 v[18:33], v[70:73], v[86:89], v[18:33]
	ds_read_b64_tr_b16 v[86:87], v0 offset:0x1600
	ds_read_b64_tr_b16 v[88:89], v0 offset:0x1e00
	v_mfma_f32_32x32x16_bf16 v[18:33], v[74:77], v[90:93], v[18:33]
	ds_read_b64_tr_b16 v[90:91], v0 offset:0x2600
	ds_read_b64_tr_b16 v[92:93], v0 offset:0x2e00
	v_mfma_f32_32x32x16_bf16 v[18:33], v[78:81], v[94:97], v[18:33]
	ds_read_b64_tr_b16 v[94:95], v0 offset:0x3600
	ds_read_b64_tr_b16 v[96:97], v0 offset:0x3e00
	s_waitcnt lgkmcnt(0)
	v_mfma_f32_32x32x16_bf16 v[2:17], v[66:69], v[82:85], v[2:17]
	s_cmp_gt_i32 s95, s22
	s_cselect_b64 s[0:1], -1, 0
	s_cmp_lt_i32 s15, s22
	s_cselect_b64 vcc, -1, 0
	v_mov_b32_e32 v232, v160
	v_mfma_f32_32x32x16_bf16 v[2:17], v[70:73], v[86:89], v[2:17]
	v_mfma_f32_32x32x16_bf16 v[2:17], v[74:77], v[90:93], v[2:17]
	v_mfma_f32_32x32x16_bf16 v[2:17], v[78:81], v[94:97], v[2:17]
	s_setprio 1
	s_and_saveexec_b64 s[58:59], vcc
	s_cbranch_execz .LBB0_181
	s_cmp_gt_i32 s91, s23
	s_cselect_b64 vcc, -1, 0
	s_mov_b64 s[62:63], -1
	s_and_saveexec_b64 s[60:61], vcc
	s_cbranch_execz .LBB0_180
	v_add_u32_e32 v230, s77, v225
	v_add_u32_e32 v66, 64, v230
	v_add_u32_e32 v68, 0x41, v230
	v_add_u32_e32 v70, 0x42, v230
	v_add_u32_e32 v72, 0x43, v230
	v_med3_i32 v67, v66, s39, v198
	v_med3_i32 v66, v66, s33, v199
	v_med3_i32 v69, v68, s39, v198
	v_med3_i32 v68, v68, s33, v199
	v_med3_i32 v71, v70, s39, v198
	v_med3_i32 v70, v70, s33, v199
	v_med3_i32 v73, v72, s39, v198
	v_med3_i32 v72, v72, s33, v199
	v_lshl_add_u32 v67, v67, 2, s76
	v_lshl_add_u32 v66, v66, 2, s76
	v_lshl_add_u32 v69, v69, 2, s76
	v_lshl_add_u32 v68, v68, 2, s76
	v_lshl_add_u32 v70, v70, 2, s76
	v_lshl_add_u32 v72, v72, 2, s76
	v_lshl_add_u32 v71, v71, 2, s76
	v_lshl_add_u32 v73, v73, 2, s76
	ds_read_b32 v194, v67 offset:516
	ds_read_b32 v66, v66 offset:644
	ds_read_b32 v195, v69 offset:516
	ds_read_b32 v67, v68 offset:644
	ds_read_b32 v232, v71 offset:516
	ds_read_b32 v68, v70 offset:644
	ds_read_b32 v233, v73 offset:516
	ds_read_b32 v69, v72 offset:644
	v_add_u32_e32 v70, 0x48, v230
	v_add_u32_e32 v72, 0x49, v230
	v_add_u32_e32 v74, 0x4a, v230
	v_add_u32_e32 v76, 0x4b, v230
	v_med3_i32 v71, v70, s39, v198
	v_med3_i32 v70, v70, s33, v199
	v_med3_i32 v73, v72, s39, v198
	v_med3_i32 v72, v72, s33, v199
	v_med3_i32 v75, v74, s39, v198
	v_med3_i32 v74, v74, s33, v199
	v_med3_i32 v77, v76, s39, v198
	v_med3_i32 v76, v76, s33, v199
	v_lshl_add_u32 v71, v71, 2, s76
	v_lshl_add_u32 v70, v70, 2, s76
	v_lshl_add_u32 v73, v73, 2, s76
	v_lshl_add_u32 v72, v72, 2, s76
	v_lshl_add_u32 v74, v74, 2, s76
	v_lshl_add_u32 v76, v76, 2, s76
	v_lshl_add_u32 v75, v75, 2, s76
	v_lshl_add_u32 v77, v77, 2, s76
	ds_read_b32 v234, v71 offset:516
	ds_read_b32 v70, v70 offset:644
	ds_read_b32 v235, v73 offset:516
	ds_read_b32 v71, v72 offset:644
	ds_read_b32 v236, v75 offset:516
	ds_read_b32 v72, v74 offset:644
	ds_read_b32 v237, v77 offset:516
	ds_read_b32 v73, v76 offset:644
	v_add_u32_e32 v74, 0x50, v230
	v_add_u32_e32 v76, 0x51, v230
	v_add_u32_e32 v78, 0x52, v230
	v_add_u32_e32 v80, 0x53, v230
	v_med3_i32 v75, v74, s39, v198
	v_med3_i32 v74, v74, s33, v199
	v_med3_i32 v77, v76, s39, v198
	v_med3_i32 v76, v76, s33, v199
	v_med3_i32 v79, v78, s39, v198
	v_med3_i32 v78, v78, s33, v199
	v_med3_i32 v81, v80, s39, v198
	v_med3_i32 v80, v80, s33, v199
	v_lshl_add_u32 v75, v75, 2, s76
	v_lshl_add_u32 v74, v74, 2, s76
	v_lshl_add_u32 v77, v77, 2, s76
	v_lshl_add_u32 v76, v76, 2, s76
	v_lshl_add_u32 v78, v78, 2, s76
	v_lshl_add_u32 v80, v80, 2, s76
	v_lshl_add_u32 v79, v79, 2, s76
	v_lshl_add_u32 v81, v81, 2, s76
	ds_read_b32 v238, v75 offset:516
	ds_read_b32 v74, v74 offset:644
	ds_read_b32 v239, v77 offset:516
	ds_read_b32 v75, v76 offset:644
	ds_read_b32 v240, v79 offset:516
	ds_read_b32 v76, v78 offset:644
	ds_read_b32 v241, v81 offset:516
	ds_read_b32 v77, v80 offset:644
	v_add_u32_e32 v78, 0x58, v230
	v_add_u32_e32 v80, 0x59, v230
	v_add_u32_e32 v82, 0x5a, v230
	v_med3_i32 v79, v78, s39, v198
	v_med3_i32 v78, v78, s33, v199
	v_med3_i32 v81, v80, s39, v198
	v_med3_i32 v80, v80, s33, v199
	v_med3_i32 v83, v82, s39, v198
	v_med3_i32 v82, v82, s33, v199
	v_add_u32_e32 v84, 0x5b, v230
	s_waitcnt lgkmcnt(14)
; template <int MODE>
; __device__ __forceinline__ void partialSM(f32x16& p0, f32x16& p1, float& m_reg, float& mn, float& alpha, int relh, int relw_min, int relw_max, const float* lut) {
;     ...
;     if (nearT) {
; #pragma unroll
;       for (int r = 0; r < 16; ++r) { const int i0 = relh + (r & 3) + 8 * (r >> 2);
;         const int a0 = min(max(i0, -129), 129) + 129, a1 = min(max(i0 + 32, -129), 129) + 129;
;         p0[r] = fmaf(p0[r], C, lut[a0]); p1[r] = fmaf(p1[r], C, lut[a1]); }
;     } else {
; #pragma unroll
;       for (int r = 0; r < 16; ++r) { p0[r] = fmaf(p0[r], C, cfar); p1[r] = fmaf(p1[r], C, cfar); }
;     }
;     float pmax = p0[0];
; #pragma unroll
;     for (int r = 1; r < 16; ++r) pmax = fmaxf(pmax, p0[r]);
; #pragma unroll
;     for (int r = 0; r < 16; ++r) pmax = fmaxf(pmax, p1[r]);
;     { auto rr = __builtin_amdgcn_permlane32_swap(__float_as_uint(pmax), __float_as_uint(pmax), false, false);
;       pmax = fmaxf(__uint_as_float(rr[0]), __uint_as_float(rr[1])); }
;     if (__builtin_expect(__all(pmax - m_reg <= THR2), 1)) { mn = m_reg; alpha = 1.f; }
;     else { mn = fmaxf(m_reg, pmax); alpha = __builtin_amdgcn_exp2f(m_reg - mn); m_reg = mn; }
; #pragma unroll
;     for (int r = 0; r < 16; ++r) p0[r] = __builtin_amdgcn_exp2f(p0[r] - mn);
; #pragma unroll
;     for (int r = 0; r < 16; ++r) p1[r] = p1[r] - mn;
	v_fmac_f32_e32 v194, 0x3e38aa3b, v114
	v_fmac_f32_e32 v195, 0x3e38aa3b, v115
	v_lshl_add_u32 v79, v79, 2, s76
	v_lshl_add_u32 v78, v78, 2, s76
	v_lshl_add_u32 v81, v81, 2, s76
	v_lshl_add_u32 v80, v80, 2, s76
	v_lshl_add_u32 v82, v82, 2, s76
	v_med3_i32 v85, v84, s39, v198
	v_med3_i32 v84, v84, s33, v199
	v_fmac_f32_e32 v232, 0x3e38aa3b, v116
	v_fmac_f32_e32 v233, 0x3e38aa3b, v117
	v_lshl_add_u32 v83, v83, 2, s76
	v_lshl_add_u32 v85, v85, 2, s76
	v_lshl_add_u32 v84, v84, 2, s76
	ds_read_b32 v242, v79 offset:516
	ds_read_b32 v78, v78 offset:644
	ds_read_b32 v243, v81 offset:516
	ds_read_b32 v79, v80 offset:644
	ds_read_b32 v244, v83 offset:516
	ds_read_b32 v80, v82 offset:644
	ds_read_b32 v245, v85 offset:516
	ds_read_b32 v81, v84 offset:644
	v_max_f32_e32 v82, v194, v195
	v_fmac_f32_e32 v234, 0x3e38aa3b, v118
	s_waitcnt lgkmcnt(14)
	v_fmac_f32_e32 v235, 0x3e38aa3b, v119
	v_max3_f32 v82, v82, v232, v233
	v_fmac_f32_e32 v236, 0x3e38aa3b, v120
	v_fmac_f32_e32 v237, 0x3e38aa3b, v121
	v_max3_f32 v82, v82, v234, v235
	v_fmac_f32_e32 v238, 0x3e38aa3b, v122
	s_waitcnt lgkmcnt(13)
	v_fmac_f32_e32 v239, 0x3e38aa3b, v123
	v_max3_f32 v82, v82, v236, v237
	s_waitcnt lgkmcnt(11)
	v_fmac_f32_e32 v240, 0x3e38aa3b, v124
	s_waitcnt lgkmcnt(9)
	v_fmac_f32_e32 v241, 0x3e38aa3b, v125
	v_max3_f32 v82, v82, v238, v239
	s_waitcnt lgkmcnt(7)
	v_fmac_f32_e32 v242, 0x3e38aa3b, v126
	s_waitcnt lgkmcnt(5)
	v_fmac_f32_e32 v243, 0x3e38aa3b, v127
	v_max3_f32 v82, v82, v240, v241
	s_waitcnt lgkmcnt(3)
	v_fmac_f32_e32 v244, 0x3e38aa3b, v128
	s_waitcnt lgkmcnt(1)
	v_fmac_f32_e32 v245, 0x3e38aa3b, v129
	v_max3_f32 v82, v82, v242, v243
	v_max3_f32 v84, v82, v244, v245
	v_pk_fma_f32 v[82:83], v[98:99], s[48:49], v[66:67] op_sel_hi:[1,0,1]
	v_pk_fma_f32 v[86:87], v[102:103], s[48:49], v[70:71] op_sel_hi:[1,0,1]
	v_max3_f32 v66, v84, v82, v83
	v_pk_fma_f32 v[84:85], v[100:101], s[48:49], v[68:69] op_sel_hi:[1,0,1]
	v_pk_fma_f32 v[88:89], v[104:105], s[48:49], v[72:73] op_sel_hi:[1,0,1]
	v_max3_f32 v66, v66, v84, v85
	v_max3_f32 v66, v66, v86, v87
	v_max3_f32 v66, v66, v88, v89
	v_pk_fma_f32 v[90:91], v[106:107], s[48:49], v[74:75] op_sel_hi:[1,0,1]
	v_pk_fma_f32 v[92:93], v[108:109], s[48:49], v[76:77] op_sel_hi:[1,0,1]
	v_max3_f32 v66, v66, v90, v91
	v_max3_f32 v66, v66, v92, v93
	v_pk_fma_f32 v[94:95], v[110:111], s[48:49], v[78:79] op_sel_hi:[1,0,1]
	s_waitcnt lgkmcnt(0)
	v_pk_fma_f32 v[96:97], v[112:113], s[48:49], v[80:81] op_sel_hi:[1,0,1]
	v_max3_f32 v66, v66, v94, v95
	v_max3_f32 v66, v66, v96, v97
	v_mov_b32_e32 v67, v66
	s_nop 1
	v_permlane32_swap_b32_e32 v66, v67
	v_max_f32_e32 v66, v66, v67
	v_sub_f32_e32 v67, v66, v222
	v_cmp_ge_f32_e32 vcc, s94, v67
	v_max_f32_e32 v66, v222, v66
	v_sub_f32_e32 v67, v222, v66
	v_exp_f32_e32 v67, v67
	s_cmp_eq_u64 vcc, exec
	s_cselect_b64 vcc, -1, 0
	v_cndmask_b32_e32 v231, v66, v222, vcc
	v_cndmask_b32_e64 v229, v67, 1.0, vcc
	v_sub_f32_e32 v66, v194, v231
	v_sub_f32_e32 v67, v195, v231
	v_sub_f32_e32 v68, v232, v231
	v_sub_f32_e32 v69, v233, v231
	v_sub_f32_e32 v70, v234, v231
	v_sub_f32_e32 v71, v235, v231
	v_sub_f32_e32 v72, v236, v231
	v_sub_f32_e32 v73, v237, v231
	v_sub_f32_e32 v74, v238, v231
	v_sub_f32_e32 v75, v239, v231
	v_sub_f32_e32 v76, v240, v231
	v_sub_f32_e32 v77, v241, v231
	v_sub_f32_e32 v78, v242, v231
	v_sub_f32_e32 v79, v243, v231
	v_sub_f32_e32 v80, v244, v231
	v_sub_f32_e32 v81, v245, v231
	v_exp_f32_e32 v66, v66
	v_exp_f32_e32 v67, v67
	v_exp_f32_e32 v68, v68
	v_exp_f32_e32 v69, v69
	v_exp_f32_e32 v70, v70
	v_exp_f32_e32 v71, v71
	v_exp_f32_e32 v72, v72
	v_exp_f32_e32 v73, v73
	v_exp_f32_e32 v74, v74
	v_exp_f32_e32 v75, v75
	v_exp_f32_e32 v76, v76
	v_exp_f32_e32 v77, v77
	v_exp_f32_e32 v78, v78
	v_exp_f32_e32 v79, v79
	v_exp_f32_e32 v80, v80
	v_exp_f32_e32 v81, v81
	v_sub_f32_e32 v97, v97, v231
	v_sub_f32_e32 v96, v96, v231
	v_sub_f32_e32 v95, v95, v231
	v_sub_f32_e32 v94, v94, v231
	v_sub_f32_e32 v93, v93, v231
	v_sub_f32_e32 v92, v92, v231
	v_sub_f32_e32 v91, v91, v231
	v_sub_f32_e32 v90, v90, v231
	v_sub_f32_e32 v89, v89, v231
	v_sub_f32_e32 v88, v88, v231
	v_sub_f32_e32 v87, v87, v231
	v_sub_f32_e32 v86, v86, v231
	v_sub_f32_e32 v85, v85, v231
	v_sub_f32_e32 v84, v84, v231
	v_sub_f32_e32 v83, v83, v231
	v_sub_f32_e32 v82, v82, v231
	s_xor_b64 s[62:63], exec, -1

; #define SBAR() __builtin_amdgcn_sched_barrier(0)
; template <int MODE>
; __device__ __forceinline__ void partialSM(f32x16& p0, f32x16& p1, float& m_reg, float& mn, float& alpha, int relh, int relw_min, int relw_max, const float* lut) {
;     ...
;     if (nearT) {
; #pragma unroll
;       for (int r = 0; r < 16; ++r) { const int i0 = relh + (r & 3) + 8 * (r >> 2);
;         const int a0 = min(max(i0, -129), 129) + 129, a1 = min(max(i0 + 32, -129), 129) + 129;
;         p0[r] = fmaf(p0[r], C, lut[a0]); p1[r] = fmaf(p1[r], C, lut[a1]); }
; template <int OFF> __device__ __forceinline__ s16x4 tr_read(int vb) {
;   s16x4 r; asm volatile("ds_read_b64_tr_b16 %0, %1 offset:%2" : "=&v"(r) : "v"(vb), "i"(OFF) : "memory"); return r;
; }
; template <int D0> __device__ __forceinline__ void pv_one(f32x16& od, int vb, bf16x8 pa0, bf16x8 pa1, bf16x8 pa2, bf16x8 pa3) {
;   const s16x4 l0 = tr_read<v_rd_off(D0, 0, 0)>(vb), h0 = tr_read<v_rd_off(D0, 0, 1)>(vb), l1 = tr_read<v_rd_off(D0, 1, 0)>(vb), h1 = tr_read<v_rd_off(D0, 1, 1)>(vb);
;   const s16x4 l2 = tr_read<v_rd_off(D0, 2, 0)>(vb), h2 = tr_read<v_rd_off(D0, 2, 1)>(vb), l3 = tr_read<v_rd_off(D0, 3, 0)>(vb), h3 = tr_read<v_rd_off(D0, 3, 1)>(vb);
;   asm volatile("s_waitcnt lgkmcnt(0)" ::: "memory"); SBAR();
;     ...
;   od = __builtin_amdgcn_mfma_f32_32x32x16_bf16(pa0, PK(l0, h0), od, 0, 0, 0);
;   od = __builtin_amdgcn_mfma_f32_32x32x16_bf16(pa1, PK(l1, h1), od, 0, 0, 0);
;   od = __builtin_amdgcn_mfma_f32_32x32x16_bf16(pa2, PK(l2, h2), od, 0, 0, 0);
;   od = __builtin_amdgcn_mfma_f32_32x32x16_bf16(pa3, PK(l3, h3), od, 0, 0, 0);
;     ...
; }
; __device__ __forceinline__ void pv_d0(f32x16* o, int vb, bf16x8 pa0, bf16x8 pa1, bf16x8 pa2, bf16x8 pa3) {
;   pv_one<0>(o[0], vb, pa0, pa1, pa2, pa3); pv_one<1>(o[1], vb, pa0, pa1, pa2, pa3); pv_one<2>(o[2], vb, pa0, pa1, pa2, pa3); pv_one<3>(o[3], vb, pa0, pa1, pa2, pa3);
.Ldp_9:
	s_setprio 0
	s_add_i32 m0, s66, s30
	s_nop 0
	global_load_lds_dwordx4 v248, s[26:27]
	s_add_i32 m0, m0, 0x400
	s_nop 0
	global_load_lds_dwordx4 v249, s[26:27]
	s_add_i32 m0, s68, s30
	s_add_i32 m0, m0, 0xc000
	s_nop 0
	global_load_lds_dwordx4 v250, s[28:29]
	s_add_i32 m0, m0, 0x400
	s_nop 0
	global_load_lds_dwordx4 v251, s[28:29]
	s_add_u32 s26, s26, 0x90000
	s_addc_u32 s27, s27, 0
	s_add_u32 s28, s28, 0x90000
	s_addc_u32 s29, s29, 0
.LBB0_189:
	v_add_u32_e32 v194, s68, v221
	ds_read_b64_tr_b16 v[82:83], v194 offset:0
	ds_read_b64_tr_b16 v[84:85], v194 offset:0x800
	ds_read_b64_tr_b16 v[86:87], v194 offset:0x1000
	ds_read_b64_tr_b16 v[88:89], v194 offset:0x1800
	ds_read_b64_tr_b16 v[90:91], v194 offset:0x2000
	ds_read_b64_tr_b16 v[92:93], v194 offset:0x2800
	ds_read_b64_tr_b16 v[94:95], v194 offset:0x3000
	ds_read_b64_tr_b16 v[96:97], v194 offset:0x3800
	s_waitcnt lgkmcnt(0)
	s_nop 0
	v_mfma_f32_32x32x16_bf16 v[50:65], v[66:69], v[82:85], v[50:65]
	ds_read_b64_tr_b16 v[82:83], v194 offset:0x200
	ds_read_b64_tr_b16 v[84:85], v194 offset:0xa00
	v_mfma_f32_32x32x16_bf16 v[50:65], v[70:73], v[86:89], v[50:65]
	ds_read_b64_tr_b16 v[86:87], v194 offset:0x1200
	ds_read_b64_tr_b16 v[88:89], v194 offset:0x1a00
	v_mfma_f32_32x32x16_bf16 v[50:65], v[74:77], v[90:93], v[50:65]
	ds_read_b64_tr_b16 v[90:91], v194 offset:0x2200
	ds_read_b64_tr_b16 v[92:93], v194 offset:0x2a00
	v_mfma_f32_32x32x16_bf16 v[50:65], v[78:81], v[94:97], v[50:65]
	ds_read_b64_tr_b16 v[94:95], v194 offset:0x3200
	ds_read_b64_tr_b16 v[96:97], v194 offset:0x3a00
	s_waitcnt lgkmcnt(0)
	v_mfma_f32_32x32x16_bf16 v[34:49], v[66:69], v[82:85], v[34:49]
	ds_read_b64_tr_b16 v[82:83], v194 offset:0x400
	ds_read_b64_tr_b16 v[84:85], v194 offset:0xc00
	v_mfma_f32_32x32x16_bf16 v[34:49], v[70:73], v[86:89], v[34:49]
	ds_read_b64_tr_b16 v[86:87], v194 offset:0x1400
	ds_read_b64_tr_b16 v[88:89], v194 offset:0x1c00
	v_mfma_f32_32x32x16_bf16 v[34:49], v[74:77], v[90:93], v[34:49]
	ds_read_b64_tr_b16 v[90:91], v194 offset:0x2400
	ds_read_b64_tr_b16 v[92:93], v194 offset:0x2c00
	v_mfma_f32_32x32x16_bf16 v[34:49], v[78:81], v[94:97], v[34:49]
	ds_read_b64_tr_b16 v[94:95], v194 offset:0x3400
	ds_read_b64_tr_b16 v[96:97], v194 offset:0x3c00
	s_waitcnt lgkmcnt(0)
	v_mfma_f32_32x32x16_bf16 v[18:33], v[66:69], v[82:85], v[18:33]
	ds_read_b64_tr_b16 v[82:83], v194 offset:0x600
	ds_read_b64_tr_b16 v[84:85], v194 offset:0xe00
	v_mfma_f32_32x32x16_bf16 v[18:33], v[70:73], v[86:89], v[18:33]
	ds_read_b64_tr_b16 v[86:87], v194 offset:0x1600
	ds_read_b64_tr_b16 v[88:89], v194 offset:0x1e00
	v_mfma_f32_32x32x16_bf16 v[18:33], v[74:77], v[90:93], v[18:33]
	ds_read_b64_tr_b16 v[90:91], v194 offset:0x2600
	ds_read_b64_tr_b16 v[92:93], v194 offset:0x2e00
	v_mfma_f32_32x32x16_bf16 v[18:33], v[78:81], v[94:97], v[18:33]
	ds_read_b64_tr_b16 v[94:95], v194 offset:0x3600
	ds_read_b64_tr_b16 v[96:97], v194 offset:0x3e00
	s_waitcnt lgkmcnt(0)
	v_mfma_f32_32x32x16_bf16 v[2:17], v[66:69], v[82:85], v[2:17]
	s_cmp_gt_i32 s95, s24
	s_cselect_b64 s[58:59], -1, 0
	s_cmp_lt_i32 s15, s24
	s_cselect_b64 vcc, -1, 0
	v_mov_b32_e32 v234, v160
	v_mfma_f32_32x32x16_bf16 v[2:17], v[70:73], v[86:89], v[2:17]
	v_mfma_f32_32x32x16_bf16 v[2:17], v[74:77], v[90:93], v[2:17]
	v_mfma_f32_32x32x16_bf16 v[2:17], v[78:81], v[94:97], v[2:17]
	s_setprio 1
	s_and_saveexec_b64 s[60:61], vcc
	s_cbranch_execz .LBB0_193
	s_cmp_gt_i32 s91, s25
	s_cselect_b64 vcc, -1, 0
	s_mov_b64 s[64:65], -1
	s_and_saveexec_b64 s[62:63], vcc
	s_cbranch_execz .LBB0_192
	v_add_u32_e32 v230, s77, v225
	v_add_u32_e32 v66, 0x80, v230
	v_add_u32_e32 v68, 0x81, v230
	v_add_u32_e32 v70, 0x82, v230
	v_add_u32_e32 v72, 0x83, v230
	v_med3_i32 v67, v66, s39, v198
	v_med3_i32 v66, v66, s33, v199
	v_med3_i32 v69, v68, s39, v198
	v_med3_i32 v68, v68, s33, v199
	v_med3_i32 v71, v70, s39, v198
	v_med3_i32 v70, v70, s33, v199
	v_med3_i32 v73, v72, s39, v198
	v_med3_i32 v72, v72, s33, v199
	v_lshl_add_u32 v67, v67, 2, s76
	v_lshl_add_u32 v66, v66, 2, s76
	v_lshl_add_u32 v69, v69, 2, s76
	v_lshl_add_u32 v68, v68, 2, s76
	v_lshl_add_u32 v70, v70, 2, s76
	v_lshl_add_u32 v72, v72, 2, s76
	v_lshl_add_u32 v71, v71, 2, s76
	v_lshl_add_u32 v73, v73, 2, s76
	ds_read_b32 v194, v67 offset:516
	ds_read_b32 v66, v66 offset:644
	ds_read_b32 v195, v69 offset:516
	ds_read_b32 v67, v68 offset:644
	ds_read_b32 v234, v71 offset:516
	ds_read_b32 v68, v70 offset:644
	ds_read_b32 v235, v73 offset:516
	ds_read_b32 v69, v72 offset:644
	v_add_u32_e32 v70, 0x88, v230
	v_add_u32_e32 v72, 0x89, v230
	v_add_u32_e32 v74, 0x8a, v230
	v_add_u32_e32 v76, 0x8b, v230
	v_med3_i32 v71, v70, s39, v198
	v_med3_i32 v70, v70, s33, v199
	v_med3_i32 v73, v72, s39, v198
	v_med3_i32 v72, v72, s33, v199
	v_med3_i32 v75, v74, s39, v198
	v_med3_i32 v74, v74, s33, v199
	v_med3_i32 v77, v76, s39, v198
	v_med3_i32 v76, v76, s33, v199
	v_lshl_add_u32 v71, v71, 2, s76
	v_lshl_add_u32 v70, v70, 2, s76
	v_lshl_add_u32 v73, v73, 2, s76
	v_lshl_add_u32 v72, v72, 2, s76
	v_lshl_add_u32 v74, v74, 2, s76
	v_lshl_add_u32 v76, v76, 2, s76
	v_lshl_add_u32 v75, v75, 2, s76
	v_lshl_add_u32 v77, v77, 2, s76
	ds_read_b32 v236, v71 offset:516
	ds_read_b32 v70, v70 offset:644
	ds_read_b32 v237, v73 offset:516
	ds_read_b32 v71, v72 offset:644
	ds_read_b32 v238, v75 offset:516
	ds_read_b32 v72, v74 offset:644
	ds_read_b32 v239, v77 offset:516
	ds_read_b32 v73, v76 offset:644
	v_add_u32_e32 v74, 0x90, v230
	v_add_u32_e32 v76, 0x91, v230
	v_add_u32_e32 v78, 0x92, v230
	v_add_u32_e32 v80, 0x93, v230
	v_med3_i32 v75, v74, s39, v198
	v_med3_i32 v74, v74, s33, v199
	v_med3_i32 v77, v76, s39, v198
	v_med3_i32 v76, v76, s33, v199
	v_med3_i32 v79, v78, s39, v198
	v_med3_i32 v78, v78, s33, v199
	v_med3_i32 v81, v80, s39, v198
	v_med3_i32 v80, v80, s33, v199
	v_lshl_add_u32 v75, v75, 2, s76
	v_lshl_add_u32 v74, v74, 2, s76
	v_lshl_add_u32 v77, v77, 2, s76
	v_lshl_add_u32 v76, v76, 2, s76
	v_lshl_add_u32 v78, v78, 2, s76
	v_lshl_add_u32 v80, v80, 2, s76
	v_lshl_add_u32 v79, v79, 2, s76
	v_lshl_add_u32 v81, v81, 2, s76
	ds_read_b32 v240, v75 offset:516
	ds_read_b32 v74, v74 offset:644
	ds_read_b32 v241, v77 offset:516
	ds_read_b32 v75, v76 offset:644
	ds_read_b32 v242, v79 offset:516
	ds_read_b32 v76, v78 offset:644
	ds_read_b32 v243, v81 offset:516
	ds_read_b32 v77, v80 offset:644
	v_add_u32_e32 v78, 0x98, v230
	v_add_u32_e32 v80, 0x99, v230
	v_add_u32_e32 v82, 0x9a, v230
	v_med3_i32 v79, v78, s39, v198
	v_med3_i32 v78, v78, s33, v199
	v_med3_i32 v81, v80, s39, v198
	v_med3_i32 v80, v80, s33, v199
	v_med3_i32 v83, v82, s39, v198
	v_med3_i32 v82, v82, s33, v199
	v_add_u32_e32 v84, 0x9b, v230
	s_waitcnt lgkmcnt(14)
; template <int MODE>
; __device__ __forceinline__ void partialSM(f32x16& p0, f32x16& p1, float& m_reg, float& mn, float& alpha, int relh, int relw_min, int relw_max, const float* lut) {
;     ...
;     if (nearT) {
; #pragma unroll
;       for (int r = 0; r < 16; ++r) { const int i0 = relh + (r & 3) + 8 * (r >> 2);
;         const int a0 = min(max(i0, -129), 129) + 129, a1 = min(max(i0 + 32, -129), 129) + 129;
;         p0[r] = fmaf(p0[r], C, lut[a0]); p1[r] = fmaf(p1[r], C, lut[a1]); }
;     } else {
; #pragma unroll
;       for (int r = 0; r < 16; ++r) { p0[r] = fmaf(p0[r], C, cfar); p1[r] = fmaf(p1[r], C, cfar); }
;     }
;     float pmax = p0[0];
; #pragma unroll
;     for (int r = 1; r < 16; ++r) pmax = fmaxf(pmax, p0[r]);
; #pragma unroll
;     for (int r = 0; r < 16; ++r) pmax = fmaxf(pmax, p1[r]);
;     { auto rr = __builtin_amdgcn_permlane32_swap(__float_as_uint(pmax), __float_as_uint(pmax), false, false);
;       pmax = fmaxf(__uint_as_float(rr[0]), __uint_as_float(rr[1])); }
;     if (__builtin_expect(__all(pmax - m_reg <= THR2), 1)) { mn = m_reg; alpha = 1.f; }
;     else { mn = fmaxf(m_reg, pmax); alpha = __builtin_amdgcn_exp2f(m_reg - mn); m_reg = mn; }
; #pragma unroll
;     for (int r = 0; r < 16; ++r) p0[r] = __builtin_amdgcn_exp2f(p0[r] - mn);
; #pragma unroll
;     for (int r = 0; r < 16; ++r) p1[r] = p1[r] - mn;
	v_fmac_f32_e32 v194, 0x3e38aa3b, v114
	v_fmac_f32_e32 v195, 0x3e38aa3b, v115
	v_lshl_add_u32 v79, v79, 2, s76
	v_lshl_add_u32 v78, v78, 2, s76
	v_lshl_add_u32 v81, v81, 2, s76
	v_lshl_add_u32 v80, v80, 2, s76
	v_lshl_add_u32 v82, v82, 2, s76
	v_med3_i32 v85, v84, s39, v198
	v_med3_i32 v84, v84, s33, v199
	v_fmac_f32_e32 v234, 0x3e38aa3b, v116
	v_fmac_f32_e32 v235, 0x3e38aa3b, v117
	v_lshl_add_u32 v83, v83, 2, s76
	v_lshl_add_u32 v85, v85, 2, s76
	v_lshl_add_u32 v84, v84, 2, s76
	ds_read_b32 v230, v79 offset:516
	ds_read_b32 v78, v78 offset:644
	ds_read_b32 v244, v81 offset:516
	ds_read_b32 v79, v80 offset:644
	ds_read_b32 v245, v83 offset:516
	ds_read_b32 v80, v82 offset:644
	ds_read_b32 v246, v85 offset:516
	ds_read_b32 v81, v84 offset:644
	v_max_f32_e32 v82, v194, v195
	v_fmac_f32_e32 v236, 0x3e38aa3b, v118
	s_waitcnt lgkmcnt(14)
	v_fmac_f32_e32 v237, 0x3e38aa3b, v119
	v_max3_f32 v82, v82, v234, v235
	v_fmac_f32_e32 v238, 0x3e38aa3b, v120
	v_fmac_f32_e32 v239, 0x3e38aa3b, v121
	v_max3_f32 v82, v82, v236, v237
	v_fmac_f32_e32 v240, 0x3e38aa3b, v122
	s_waitcnt lgkmcnt(13)
	v_fmac_f32_e32 v241, 0x3e38aa3b, v123
	v_max3_f32 v82, v82, v238, v239
	s_waitcnt lgkmcnt(11)
	v_fmac_f32_e32 v242, 0x3e38aa3b, v124
	s_waitcnt lgkmcnt(9)
	v_fmac_f32_e32 v243, 0x3e38aa3b, v125
	v_max3_f32 v82, v82, v240, v241
	s_waitcnt lgkmcnt(7)
	v_fmac_f32_e32 v230, 0x3e38aa3b, v126
	s_waitcnt lgkmcnt(5)
	v_fmac_f32_e32 v244, 0x3e38aa3b, v127
	v_max3_f32 v82, v82, v242, v243
	s_waitcnt lgkmcnt(3)
	v_fmac_f32_e32 v245, 0x3e38aa3b, v128
	s_waitcnt lgkmcnt(1)
	v_fmac_f32_e32 v246, 0x3e38aa3b, v129
	v_max3_f32 v82, v82, v230, v244
	v_max3_f32 v84, v82, v245, v246
	v_pk_fma_f32 v[82:83], v[98:99], s[48:49], v[66:67] op_sel_hi:[1,0,1]
	v_pk_fma_f32 v[86:87], v[102:103], s[48:49], v[70:71] op_sel_hi:[1,0,1]
	v_max3_f32 v66, v84, v82, v83
	v_pk_fma_f32 v[84:85], v[100:101], s[48:49], v[68:69] op_sel_hi:[1,0,1]
	v_pk_fma_f32 v[88:89], v[104:105], s[48:49], v[72:73] op_sel_hi:[1,0,1]
	v_max3_f32 v66, v66, v84, v85
	v_max3_f32 v66, v66, v86, v87
	v_max3_f32 v66, v66, v88, v89
	v_pk_fma_f32 v[90:91], v[106:107], s[48:49], v[74:75] op_sel_hi:[1,0,1]
	v_pk_fma_f32 v[92:93], v[108:109], s[48:49], v[76:77] op_sel_hi:[1,0,1]
	v_max3_f32 v66, v66, v90, v91
	v_max3_f32 v66, v66, v92, v93
	v_pk_fma_f32 v[94:95], v[110:111], s[48:49], v[78:79] op_sel_hi:[1,0,1]
	s_waitcnt lgkmcnt(0)
	v_pk_fma_f32 v[96:97], v[112:113], s[48:49], v[80:81] op_sel_hi:[1,0,1]
	v_max3_f32 v66, v66, v94, v95
	v_max3_f32 v66, v66, v96, v97
	v_mov_b32_e32 v67, v66
	s_nop 1
	v_permlane32_swap_b32_e32 v66, v67
	v_max_f32_e32 v66, v66, v67
	v_sub_f32_e32 v67, v66, v231
	v_cmp_ge_f32_e32 vcc, s94, v67
	v_max_f32_e32 v66, v231, v66
	v_sub_f32_e32 v67, v231, v66
	v_exp_f32_e32 v67, v67
	s_cmp_eq_u64 vcc, exec
	s_cselect_b64 vcc, -1, 0
	v_cndmask_b32_e32 v222, v66, v231, vcc
	v_cndmask_b32_e64 v228, v67, 1.0, vcc
	v_sub_f32_e32 v66, v194, v222
	v_sub_f32_e32 v67, v195, v222
	v_sub_f32_e32 v68, v234, v222
	v_sub_f32_e32 v69, v235, v222
	v_sub_f32_e32 v70, v236, v222
	v_sub_f32_e32 v71, v237, v222
	v_sub_f32_e32 v72, v238, v222
	v_sub_f32_e32 v73, v239, v222
	v_sub_f32_e32 v74, v240, v222
	v_sub_f32_e32 v75, v241, v222
	v_sub_f32_e32 v76, v242, v222
	v_sub_f32_e32 v77, v243, v222
	v_sub_f32_e32 v78, v230, v222
	v_sub_f32_e32 v79, v244, v222
	v_sub_f32_e32 v80, v245, v222
	v_sub_f32_e32 v81, v246, v222
	v_exp_f32_e32 v66, v66
	v_exp_f32_e32 v67, v67
	v_exp_f32_e32 v68, v68
	v_exp_f32_e32 v69, v69
	v_exp_f32_e32 v70, v70
	v_exp_f32_e32 v71, v71
	v_exp_f32_e32 v72, v72
	v_exp_f32_e32 v73, v73
	v_exp_f32_e32 v74, v74
	v_exp_f32_e32 v75, v75
	v_exp_f32_e32 v76, v76
	v_exp_f32_e32 v77, v77
	v_exp_f32_e32 v78, v78
	v_exp_f32_e32 v79, v79
	v_exp_f32_e32 v80, v80
	v_exp_f32_e32 v81, v81
	v_sub_f32_e32 v97, v97, v222
	v_sub_f32_e32 v96, v96, v222
	v_sub_f32_e32 v95, v95, v222
	v_sub_f32_e32 v94, v94, v222
	v_sub_f32_e32 v93, v93, v222
	v_sub_f32_e32 v92, v92, v222
	v_sub_f32_e32 v91, v91, v222
	v_sub_f32_e32 v90, v90, v222
	v_sub_f32_e32 v89, v89, v222
	v_sub_f32_e32 v88, v88, v222
	v_sub_f32_e32 v87, v87, v222
	v_sub_f32_e32 v86, v86, v222
	v_sub_f32_e32 v85, v85, v222
	v_sub_f32_e32 v84, v84, v222
	v_sub_f32_e32 v83, v83, v222
	v_sub_f32_e32 v82, v82, v222
	s_xor_b64 s[64:65], exec, -1
